# prep phase: the 64 MU fold-matrix items moved from blocks 0..63 to the tail blocks 448..511 (512-block grid only)
# speedup vs baseline: 1.0142x; 1.0018x over previous
.LBB0_17:
	v_mov_b32_e32 v0, v231
	ds_read_b64 v[4:5], v1 offset:63760
	s_mov_b32 s6, s76
	s_cmp_eq_u32 s82, 0x200
	s_cbranch_scc0 .Lmu_gen
	s_sub_i32 s6, s76, 0x1c0
	s_cmp_lt_i32 s6, 0
	s_cselect_b32 s6, 64, s6
.Lmu_gen:
	s_cmp_gt_i32 s6, 63
	s_cbranch_scc1 .LBB0_26
	v_cvt_f32_i32_e32 v1, v0
	s_mov_b32 s0, 0x7f800000
	v_mov_b32_e32 v8, 0xbf1f24be
	s_movk_i32 s2, 0x1f8
	v_mul_f32_e32 v1, 0x3d000000, v1
	v_mul_f32_e64 v3, |v1|, 0.5
	v_fract_f32_e32 v6, v3
	v_add_f32_e32 v6, v6, v6
	v_cmp_neq_f32_e64 s[0:1], s0, v3
	v_and_b32_e32 v2, 0x7fffffff, v1
	v_xor_b32_e32 v2, v2, v1
	v_cndmask_b32_e64 v3, 0, v6, s[0:1]
	v_cmp_gt_f32_e64 s[0:1], |v1|, 1.0
	v_cmp_class_f32_e64 s[2:3], v1, s2
	v_cmp_gt_i32_e32 vcc, 64, v0
	v_cndmask_b32_e64 v3, |v1|, v3, s[0:1]
	v_add_f32_e32 v6, v3, v3
	v_rndne_f32_e32 v6, v6
	v_fmac_f32_e32 v3, -0.5, v6
	v_mul_f32_e32 v7, v3, v3
	v_fmac_f32_e32 v8, 0x3e75aa41, v7
	v_fmaak_f32 v8, v7, v8, 0x40234736
	v_fmaak_f32 v8, v7, v8, 0xc0a55e0e
	v_mul_f32_e32 v9, v3, v7
	v_mul_f32_e32 v8, v9, v8
	v_fmamk_f32 v3, v3, 0x40490fdb, v8
	v_mov_b32_e32 v8, 0x3e642e9d
	v_cvt_i32_f32_e32 v6, v6
	v_fmac_f32_e32 v8, 0x3d4be544, v7
	v_fmaak_f32 v8, v7, v8, 0xbfaad1da
	v_fmaak_f32 v8, v7, v8, 0x4081e0d3
	v_fmaak_f32 v8, v7, v8, 0xc09de9e6
	v_fma_f32 v7, v7, v8, 1.0
	v_and_b32_e32 v8, 1, v6
	v_lshlrev_b32_e32 v9, 30, v6
	v_cmp_eq_u32_e64 s[0:1], 0, v8
	v_and_b32_e32 v9, 0x80000000, v9
	v_xor_b32_e32 v2, v2, v9
	v_cndmask_b32_e64 v8, v7, v3, s[0:1]
	v_xor_b32_e32 v2, v2, v8
	v_mov_b32_e32 v8, 0x7fc00000
	v_and_b32_e32 v1, 2, v6
	v_cndmask_b32_e64 v10, v8, v2, s[2:3]
	v_cndmask_b32_e64 v2, -v3, v7, s[0:1]
	v_cmp_eq_u32_e64 s[0:1], 0, v1
	v_lshlrev_b32_e32 v12, 2, v0
	v_ashrrev_i32_e32 v13, 6, v0
	v_cndmask_b32_e64 v1, -v2, v2, s[0:1]
	v_cndmask_b32_e64 v11, v8, v1, s[2:3]
	v_and_b32_e32 v0, 63, v0
	v_mov_b32_e32 v1, 0
	v_lshlrev_b32_e32 v2, 2, v0
	v_mov_b32_e32 v3, v1
	s_waitcnt lgkmcnt(0)
	v_lshl_add_u64 v[4:5], v[4:5], 0, v[2:3]
	s_mov_b64 s[0:1], 0xefd4000
	v_lshl_add_u64 v[4:5], v[4:5], 0, s[0:1]
	s_movk_i32 s0, 0x104
	v_mad_u64_u32 v[6:7], s[0:1], v13, s0, v[2:3]
	s_mov_b32 s5, 0
	v_lshlrev_b32_e32 v3, 3, v13
	v_lshlrev_b32_e32 v7, 1, v13
	v_lshl_add_u32 v14, v13, 1, v13
	v_lshlrev_b32_e32 v15, 2, v13
	v_lshl_add_u32 v16, v13, 2, v13
	v_mul_lo_u32 v17, v13, 6
	v_mul_lo_u32 v18, v13, 7
	v_lshlrev_b32_e32 v0, 2, v0
